# m13 + code placement: s_nop padding so that all six GEMM K-loop heads sit at 0 mod 8 bytes (5 of 6 were at 4 mod 8)
# baseline (speedup 1.0000x reference)
.LBB0_418:
	s_ashr_i32 s51, s50, 31
	v_mov_b64_e32 v[126:127], 0
	s_lshl_b64 s[10:11], s[50:51], 19
	v_mov_b64_e32 v[128:129], 0
	s_add_u32 s52, s12, s10
	s_addc_u32 s53, s13, s11
	s_and_b64 s[10:11], s[38:39], exec
	s_cselect_b32 s34, s53, s9
	s_cselect_b32 s35, s52, s8
	s_ashr_i32 s49, s48, 31
	s_lshl_b64 s[10:11], s[48:49], 19
	s_add_u32 s56, s14, s10
	s_addc_u32 s57, s15, s11
	s_and_b64 s[10:11], s[38:39], exec
	s_cselect_b32 s36, s57, s1
	s_cselect_b32 s37, s56, s0
	s_add_u32 s49, s0, 0x100
	s_addc_u32 s51, s1, 0
	s_add_u32 s0, s8, 0x40080
	v_mov_b64_e32 v[2:3], 0
	s_addc_u32 s1, s9, 0
	s_mov_b32 s55, -2
	s_nop 0

.LBB0_527:
	s_add_u32 s80, s8, 0x100
	s_addc_u32 s81, s9, 0
	s_add_u32 s8, s70, 0xb0080
	s_addc_u32 s9, s71, 0
	v_lshl_add_u64 v[136:137], s[8:9], 0, v[132:133]
	v_lshl_add_u64 v[138:139], s[8:9], 0, v[134:135]
	s_mov_b32 s82, -2
	s_mov_b64 s[8:9], 0
	s_nop 0

.LBB0_795:
	s_ashr_i32 s57, s56, 31
	v_mov_b64_e32 v[126:127], 0
	s_lshl_b64 s[10:11], s[56:57], 19
	v_mov_b64_e32 v[128:129], 0
	s_add_u32 s58, s12, s10
	s_addc_u32 s59, s13, s11
	s_and_b64 s[10:11], s[40:41], exec
	s_cselect_b32 s36, s59, s9
	s_cselect_b32 s37, s58, s8
	s_ashr_i32 s53, s52, 31
	s_lshl_b64 s[10:11], s[52:53], 19
	s_add_u32 s60, s14, s10
	s_addc_u32 s61, s15, s11
	s_and_b64 s[10:11], s[40:41], exec
	s_cselect_b32 s42, s61, s1
	s_cselect_b32 s43, s60, s0
	s_add_u32 s53, s0, 0x100
	s_addc_u32 s54, s1, 0
	s_add_u32 s0, s8, 0x40080
	v_mov_b64_e32 v[2:3], 0
	s_addc_u32 s1, s9, 0
	s_mov_b32 s55, -2
	s_nop 0
